# also reversed cd_out conversion start (balances item counts on the phase-1 idle workgroups)
# baseline (speedup 1.0000x reference)
; #define LAS __attribute__((address_space(3)))
; __device__ __forceinline__ void conv_matrix(const float* W, int K, int N, const float* gain, bf16_t* WT, int Kd, int mode, int row_off, LAS float* scr, int lane, int gw, int NGW) {
;     const int nblk = N / 32, items = nblk * (K / 64);
;     for (int it = gw; it < items; it += NGW) {
;         const int kb = it / nblk, nb = it % nblk, k0 = 64 * kb, n0 = 32 * nb;
;         float wv[32];
; #pragma unroll
;         for (int i = 0; i < 32; ++i) wv[i] = W[(size_t)(k0 + 2 * i + (lane >> 5)) * N + n0 + (lane & 31)];
.Lskip_c2:
.LBB0_112:
	s_waitcnt lgkmcnt(0)
	v_cndmask_b32_e64 v2, 0, 1, s[16:17]
	v_cmp_ne_u32_e64 s[38:39], 1, v2
	s_andn2_b64 vcc, exec, s[16:17]
	s_cbranch_vccnz .LBB0_115
	v_readlane_b32 s9, v254, 12
	v_lshlrev_b32_e32 v4, 2, v54
	v_mov_b32_e32 v5, v0
	v_mov_b32_e32 v2, s9
	ds_read_b64 v[2:3], v2
	v_and_b32_e32 v4, 0x7c, v4
	v_add_u32_e32 v9, s5, v4
	v_lshrrev_b32_e32 v7, 3, v1
	v_lshrrev_b32_e32 v6, 5, v1
	s_waitcnt lgkmcnt(0)
	v_lshl_add_u64 v[2:3], v[2:3], 0, v[4:5]
	v_lshlrev_b32_e32 v4, 3, v1
	v_and_b32_e32 v4, 56, v4
	v_mul_u32_u24_e32 v8, 0x84, v4
	v_lshlrev_b32_e32 v4, 1, v4
	v_lshlrev_b32_e32 v10, 2, v7
	v_lshl_add_u64 v[4:5], s[0:1], 0, v[4:5]
	s_mov_b64 s[16:17], 0xc500000
	v_add3_u32 v8, s5, v8, v10
	v_mul_u32_u24_e32 v10, 0x84, v6
	v_lshl_add_u64 v[4:5], v[4:5], 0, s[16:17]
	s_lshl_b32 s12, s8, 5
	v_add_u32_e32 v9, v9, v10
	s_sub_i32 s22, s8, s4
	s_add_i32 s22, s22, -1
	s_lshl_b32 s9, s22, 5
	s_cmp_lg_u32 s58, 1
	s_cbranch_scc1 .Lskip_c3
